# v7 + the eight 1/rms table LDS reads of the Q, G1-even and G1-odd GEMM epilogues issued together at the top of the epilogue (one wait) instead of one round trip per row group
# baseline (speedup 1.0000x reference)
; #define LAS __attribute__((address_space(3)))
;     __device__ __forceinline__ void operator()(const f32x4 (&acc)[2][2][4][2], const Unit& u, int wr, int wc, int fr_, int fq_) const {
;     ...
;         const int chl = wc * 16 + 4 * fq, ch = u.pn * 64 + chl;
;         f32x4 w0, w1, w2;
;         { const int ui = (u.pn - pn0) >> 2;
;           if (u.pm == pm0 && ui >= 0 && ui < 8 && ((u.pn - pn0) & 3) == 0) { w0 = *(const LAS f32x4*)(cwl + (ui * 3 + 0) * 64 + chl); w1 = *(const LAS f32x4*)(cwl + (ui * 3 + 1) * 64 + chl); w2 = *(const LAS f32x4*)(cwl + (ui * 3 + 2) * 64 + chl); }
;           else { w0 = *(const f32x4*)(cw + ch); w1 = *(const f32x4*)(cw + 2048 + ch); w2 = *(const f32x4*)(cw + 4096 + ch); } }
;         f32x4 e[2][4]; float rsv[2][4];
; #pragma unroll
;         for (int ai = 0; ai < 2; ++ai)
; #pragma unroll
;             for (int m = 0; m < 4; ++m) {
;                 const int rb = 8 * ai + 4 * wr + m, row = u.pm * 256 + 16 * rb + fr;
;                 const float rs = u.pm == pm0 ? rtab[16 * rb + fr] : rstd16(rsq + (size_t)row * 16); rsv[ai][m] = rs;
.LBB0_698:
	s_sub_i32 s13, s10, s79
	s_ashr_i32 s12, s13, 2
	v_mov_b32_e32 v171, v166
	v_readlane_b32 s100, v254, 53
	v_readlane_b32 s101, v255, 6
	s_nop 1
	v_lshl_add_u32 v196, v171, 2, s100
	v_lshl_add_u32 v197, v171, 2, s101
	ds_read_b32 v188, v196
	ds_read_b32 v189, v197
	v_readlane_b32 s100, v254, 55
	v_readlane_b32 s101, v254, 59
	s_nop 1
	v_lshl_add_u32 v196, v171, 2, s100
	v_lshl_add_u32 v197, v171, 2, s101
	ds_read_b32 v190, v196
	ds_read_b32 v191, v197
	v_readlane_b32 s100, v254, 61
	v_readlane_b32 s101, v254, 57
	s_nop 1
	v_lshl_add_u32 v196, v171, 2, s100
	v_lshl_add_u32 v197, v171, 2, s101
	ds_read_b32 v192, v196
	ds_read_b32 v193, v197
	v_readlane_b32 s100, v255, 1
	v_readlane_b32 s101, v254, 37
	s_nop 1
	v_lshl_add_u32 v196, v171, 2, s100
	v_lshl_add_u32 v197, v171, 2, s101
	ds_read_b32 v194, v196
	ds_read_b32 v195, v197
	v_mov_b32_e32 v32, v167
	s_cmp_lg_u32 s66, s24
	s_cselect_b64 s[14:15], -1, 0
	v_lshl_add_u32 v158, v32, 2, s1
	s_cmp_eq_u32 s66, s24
	v_lshl_add_u32 v156, s10, 6, v158
	s_cselect_b64 s[10:11], -1, 0
	s_cmp_lt_u32 s12, 8
	s_cselect_b64 s[16:17], -1, 0
	s_and_b32 s13, s13, 3
	s_cmp_eq_u32 s13, 0
	s_cselect_b64 s[68:69], -1, 0
	s_and_b64 s[16:17], s[16:17], s[68:69]
	s_and_b64 s[16:17], s[10:11], s[16:17]
	s_mov_b64 s[10:11], -1
	s_andn2_b64 vcc, exec, s[16:17]
	v_ashrrev_i32_e32 v157, 31, v156
	s_movk_i32 s34, 0xf200
	s_cbranch_vccz .LBB0_700
	v_readlane_b32 s10, v254, 39
	v_lshlrev_b64 v[32:33], 2, v[156:157]
	v_readlane_b32 s11, v254, 40
	v_lshl_add_u64 v[34:35], s[28:29], 0, v[32:33]
	s_nop 0
	v_lshl_add_u64 v[36:37], s[10:11], 0, v[32:33]
	v_readlane_b32 s10, v254, 46
	v_readlane_b32 s11, v254, 47
	global_load_dwordx4 v[40:43], v[34:35], off
	s_nop 0
	global_load_dwordx4 v[36:39], v[36:37], off
	v_lshl_add_u64 v[32:33], s[10:11], 0, v[32:33]
	global_load_dwordx4 v[32:35], v[32:33], off
	s_mov_b64 s[10:11], 0

;     __device__ __forceinline__ void operator()(const f32x4 (&acc)[2][2][4][2], const Unit& u, int wr, int wc, int fr_, int fq_) const {
;     ...
;                 const int rb = 8 * ai + 4 * wr + m, row = u.pm * 256 + 16 * rb + fr;
;                 const float rs = u.pm == pm0 ? rtab[16 * rb + fr] : rstd16(rsq + (size_t)row * 16); rsv[ai][m] = rs;
.LBB0_704:
	s_andn2_b64 vcc, exec, s[10:11]
	s_cbranch_vccnz .LBB0_706
	v_readlane_b32 s10, v254, 53
	s_nop 1
	v_lshl_add_u32 v159, v171, 2, s10
	s_waitcnt lgkmcnt(0)
	v_mov_b32_e32 v164, v188

;     __device__ __forceinline__ void operator()(const f32x4 (&acc)[2][2][4][2], const Unit& u, int wr, int wc, int fr_, int fq_) const {
;     ...
;                 const int rb = 8 * ai + 4 * wr + m, row = u.pm * 256 + 16 * rb + fr;
;                 const float rs = u.pm == pm0 ? rtab[16 * rb + fr] : rstd16(rsq + (size_t)row * 16); rsv[ai][m] = rs;
.LBB0_710:
	s_andn2_b64 vcc, exec, s[16:17]
	s_cbranch_vccnz .LBB0_712
	v_readlane_b32 s14, v255, 6
	s_nop 1
	v_lshl_add_u32 v136, v171, 2, s14
	s_waitcnt lgkmcnt(0)
	v_mov_b32_e32 v162, v189

;     __device__ __forceinline__ void operator()(const f32x4 (&acc)[2][2][4][2], const Unit& u, int wr, int wc, int fr_, int fq_) const {
;     ...
;                 const int rb = 8 * ai + 4 * wr + m, row = u.pm * 256 + 16 * rb + fr;
;                 const float rs = u.pm == pm0 ? rtab[16 * rb + fr] : rstd16(rsq + (size_t)row * 16); rsv[ai][m] = rs;
.LBB0_716:
	s_andn2_b64 vcc, exec, s[14:15]
	s_cbranch_vccnz .LBB0_718
	v_readlane_b32 s14, v254, 55
	s_nop 1
	v_lshl_add_u32 v128, v171, 2, s14
	s_waitcnt lgkmcnt(0)
	v_mov_b32_e32 v158, v190

;     __device__ __forceinline__ void operator()(const f32x4 (&acc)[2][2][4][2], const Unit& u, int wr, int wc, int fr_, int fq_) const {
;     ...
;                 const int rb = 8 * ai + 4 * wr + m, row = u.pm * 256 + 16 * rb + fr;
;                 const float rs = u.pm == pm0 ? rtab[16 * rb + fr] : rstd16(rsq + (size_t)row * 16); rsv[ai][m] = rs;
.LBB0_722:
	s_andn2_b64 vcc, exec, s[14:15]
	s_cbranch_vccnz .LBB0_724
	v_readlane_b32 s14, v254, 59
	s_nop 1
	v_lshl_add_u32 v120, v171, 2, s14
	s_waitcnt lgkmcnt(0)
	v_mov_b32_e32 v136, v191

;     __device__ __forceinline__ void operator()(const f32x4 (&acc)[2][2][4][2], const Unit& u, int wr, int wc, int fr_, int fq_) const {
;     ...
;                 const int rb = 8 * ai + 4 * wr + m, row = u.pm * 256 + 16 * rb + fr;
;                 const float rs = u.pm == pm0 ? rtab[16 * rb + fr] : rstd16(rsq + (size_t)row * 16); rsv[ai][m] = rs;
.LBB0_728:
	s_andn2_b64 vcc, exec, s[14:15]
	s_cbranch_vccnz .LBB0_730
	v_readlane_b32 s14, v254, 61
	s_nop 1
	v_lshl_add_u32 v112, v171, 2, s14
	s_waitcnt lgkmcnt(0)
	v_mov_b32_e32 v128, v192

;     __device__ __forceinline__ void operator()(const f32x4 (&acc)[2][2][4][2], const Unit& u, int wr, int wc, int fr_, int fq_) const {
;     ...
;                 const int rb = 8 * ai + 4 * wr + m, row = u.pm * 256 + 16 * rb + fr;
;                 const float rs = u.pm == pm0 ? rtab[16 * rb + fr] : rstd16(rsq + (size_t)row * 16); rsv[ai][m] = rs;
.LBB0_734:
	s_andn2_b64 vcc, exec, s[14:15]
	s_cbranch_vccnz .LBB0_736
	v_readlane_b32 s14, v254, 57
	s_nop 1
	v_lshl_add_u32 v108, v171, 2, s14
	s_waitcnt lgkmcnt(0)
	v_mov_b32_e32 v120, v193

;     __device__ __forceinline__ void operator()(const f32x4 (&acc)[2][2][4][2], const Unit& u, int wr, int wc, int fr_, int fq_) const {
;     ...
;                 const int rb = 8 * ai + 4 * wr + m, row = u.pm * 256 + 16 * rb + fr;
;                 const float rs = u.pm == pm0 ? rtab[16 * rb + fr] : rstd16(rsq + (size_t)row * 16); rsv[ai][m] = rs;
.LBB0_740:
	s_andn2_b64 vcc, exec, s[14:15]
	s_cbranch_vccnz .LBB0_742
	v_readlane_b32 s14, v255, 1
	s_nop 1
	v_lshl_add_u32 v100, v171, 2, s14
	s_waitcnt lgkmcnt(0)
	v_mov_b32_e32 v112, v194

;     __device__ __forceinline__ void operator()(const f32x4 (&acc)[2][2][4][2], const Unit& u, int wr, int wc, int fr_, int fq_) const {
;     ...
;                 const int rb = 8 * ai + 4 * wr + m, row = u.pm * 256 + 16 * rb + fr;
;                 const float rs = u.pm == pm0 ? rtab[16 * rb + fr] : rstd16(rsq + (size_t)row * 16); rsv[ai][m] = rs;
.LBB0_746:
	s_andn2_b64 vcc, exec, s[14:15]
	s_cbranch_vccnz .LBB0_748
	v_readlane_b32 s12, v254, 37
	s_nop 1
	v_lshl_add_u32 v92, v171, 2, s12
	s_waitcnt lgkmcnt(0)
	v_mov_b32_e32 v108, v195

;     __device__ __forceinline__ void operator()(const f32x4 (&acc)[2][2][4][2], const Unit& u, int wr, int wc, int fr_, int fq_) const {
;     ...
;                 const int row = u.pm * 256 + ai * 128 + wr * 64 + m * 16 + fr;
;                 const float rs = u.pm == pm0 ? rtab[ai * 128 + wr * 64 + m * 16 + fr] : rstd16(rsq + (size_t)row * 16);
.LBB0_1032:
	s_andn2_b64 vcc, exec, s[12:13]
	v_lshl_add_u32 v160, v161, 2, s83
	ds_read_b32 v174, v160
	ds_read_b32 v175, v160 offset:64
	ds_read_b32 v176, v160 offset:128
	ds_read_b32 v177, v160 offset:192
	ds_read_b32 v178, v160 offset:512
	ds_read_b32 v179, v160 offset:576
	ds_read_b32 v180, v160 offset:640
	ds_read_b32 v181, v160 offset:704
	s_cbranch_vccnz .LBB0_1034
	s_waitcnt lgkmcnt(0)
	v_mov_b32_e32 v148, v174

;     __device__ __forceinline__ void operator()(const f32x4 (&acc)[2][2][4][2], const Unit& u, int wr, int wc, int fr_, int fq_) const {
;     ...
;                 const int row = u.pm * 256 + ai * 128 + wr * 64 + m * 16 + fr;
;                 const float rs = u.pm == pm0 ? rtab[ai * 128 + wr * 64 + m * 16 + fr] : rstd16(rsq + (size_t)row * 16);
.LBB0_1053:
	s_andn2_b64 vcc, exec, s[56:57]
	s_cbranch_vccnz .LBB0_1055
	s_waitcnt lgkmcnt(0)
	v_mov_b32_e32 v114, v175

;     __device__ __forceinline__ void operator()(const f32x4 (&acc)[2][2][4][2], const Unit& u, int wr, int wc, int fr_, int fq_) const {
;     ...
;                 const int row = u.pm * 256 + ai * 128 + wr * 64 + m * 16 + fr;
;                 const float rs = u.pm == pm0 ? rtab[ai * 128 + wr * 64 + m * 16 + fr] : rstd16(rsq + (size_t)row * 16);
.LBB0_1074:
	s_andn2_b64 vcc, exec, s[16:17]
	s_cbranch_vccnz .LBB0_1076
	s_waitcnt lgkmcnt(0)
	v_mov_b32_e32 v98, v176

;     __device__ __forceinline__ void operator()(const f32x4 (&acc)[2][2][4][2], const Unit& u, int wr, int wc, int fr_, int fq_) const {
;     ...
;                 const int row = u.pm * 256 + ai * 128 + wr * 64 + m * 16 + fr;
;                 const float rs = u.pm == pm0 ? rtab[ai * 128 + wr * 64 + m * 16 + fr] : rstd16(rsq + (size_t)row * 16);
.LBB0_1095:
	s_andn2_b64 vcc, exec, s[16:17]
	s_cbranch_vccnz .LBB0_1097
	s_waitcnt lgkmcnt(0)
	v_mov_b32_e32 v82, v177

;     __device__ __forceinline__ void operator()(const f32x4 (&acc)[2][2][4][2], const Unit& u, int wr, int wc, int fr_, int fq_) const {
;     ...
;                 const int row = u.pm * 256 + ai * 128 + wr * 64 + m * 16 + fr;
;                 const float rs = u.pm == pm0 ? rtab[ai * 128 + wr * 64 + m * 16 + fr] : rstd16(rsq + (size_t)row * 16);
.LBB0_1116:
	s_andn2_b64 vcc, exec, s[16:17]
	s_cbranch_vccnz .LBB0_1118
	v_lshl_add_u32 v66, v161, 2, s84
	s_waitcnt lgkmcnt(0)
	v_mov_b32_e32 v66, v178

;     __device__ __forceinline__ void operator()(const f32x4 (&acc)[2][2][4][2], const Unit& u, int wr, int wc, int fr_, int fq_) const {
;     ...
;                 const int row = u.pm * 256 + ai * 128 + wr * 64 + m * 16 + fr;
;                 const float rs = u.pm == pm0 ? rtab[ai * 128 + wr * 64 + m * 16 + fr] : rstd16(rsq + (size_t)row * 16);
.LBB0_1137:
	s_andn2_b64 vcc, exec, s[16:17]
	s_cbranch_vccnz .LBB0_1139
	s_waitcnt lgkmcnt(0)
	v_mov_b32_e32 v50, v179

;     __device__ __forceinline__ void operator()(const f32x4 (&acc)[2][2][4][2], const Unit& u, int wr, int wc, int fr_, int fq_) const {
;     ...
;                 const int row = u.pm * 256 + ai * 128 + wr * 64 + m * 16 + fr;
;                 const float rs = u.pm == pm0 ? rtab[ai * 128 + wr * 64 + m * 16 + fr] : rstd16(rsq + (size_t)row * 16);
.LBB0_1158:
	s_andn2_b64 vcc, exec, s[16:17]
	s_cbranch_vccnz .LBB0_1160
	s_waitcnt lgkmcnt(0)
	v_mov_b32_e32 v34, v180

;     __device__ __forceinline__ void operator()(const f32x4 (&acc)[2][2][4][2], const Unit& u, int wr, int wc, int fr_, int fq_) const {
;     ...
;                 const int row = u.pm * 256 + ai * 128 + wr * 64 + m * 16 + fr;
;                 const float rs = u.pm == pm0 ? rtab[ai * 128 + wr * 64 + m * 16 + fr] : rstd16(rsq + (size_t)row * 16);
.LBB0_1179:
	s_andn2_b64 vcc, exec, s[16:17]
	s_cbranch_vccnz .LBB0_1181
	s_waitcnt lgkmcnt(0)
	v_mov_b32_e32 v18, v181

;     __device__ __forceinline__ void operator()(const f32x4 (&acc)[2][2][4][2], const Unit& u, int wr, int wc, int fr_, int fq_) const {
;     ...
;                 const int row = u.pm * 256 + ai * 128 + wr * 64 + m * 16 + fr;
;                 const float rs = u.pm == pm0 ? rtab[ai * 128 + wr * 64 + m * 16 + fr] : rstd16(rsq + (size_t)row * 16);
.LBB0_1868:
	s_andn2_b64 vcc, exec, s[40:41]
	v_lshl_add_u32 v147, v148, 2, s60
	ds_read_b32 v166, v147
	ds_read_b32 v167, v147 offset:64
	ds_read_b32 v168, v147 offset:128
	ds_read_b32 v169, v147 offset:192
	ds_read_b32 v170, v147 offset:512
	ds_read_b32 v171, v147 offset:576
	ds_read_b32 v172, v147 offset:640
	ds_read_b32 v173, v147 offset:704
	s_cbranch_vccnz .LBB0_1870
	s_waitcnt lgkmcnt(0)
	v_mov_b32_e32 v142, v166

;     __device__ __forceinline__ void operator()(const f32x4 (&acc)[2][2][4][2], const Unit& u, int wr, int wc, int fr_, int fq_) const {
;     ...
;                 const int row = u.pm * 256 + ai * 128 + wr * 64 + m * 16 + fr;
;                 const float rs = u.pm == pm0 ? rtab[ai * 128 + wr * 64 + m * 16 + fr] : rstd16(rsq + (size_t)row * 16);
.LBB0_1872:
	s_andn2_b64 vcc, exec, s[40:41]
	s_cbranch_vccnz .LBB0_1874
	s_waitcnt lgkmcnt(0)
	v_mov_b32_e32 v114, v167

;     __device__ __forceinline__ void operator()(const f32x4 (&acc)[2][2][4][2], const Unit& u, int wr, int wc, int fr_, int fq_) const {
;     ...
;                 const int row = u.pm * 256 + ai * 128 + wr * 64 + m * 16 + fr;
;                 const float rs = u.pm == pm0 ? rtab[ai * 128 + wr * 64 + m * 16 + fr] : rstd16(rsq + (size_t)row * 16);
.LBB0_1876:
	s_andn2_b64 vcc, exec, s[38:39]
	s_cbranch_vccnz .LBB0_1878
	s_waitcnt lgkmcnt(0)
	v_mov_b32_e32 v98, v168

;     __device__ __forceinline__ void operator()(const f32x4 (&acc)[2][2][4][2], const Unit& u, int wr, int wc, int fr_, int fq_) const {
;     ...
;                 const int row = u.pm * 256 + ai * 128 + wr * 64 + m * 16 + fr;
;                 const float rs = u.pm == pm0 ? rtab[ai * 128 + wr * 64 + m * 16 + fr] : rstd16(rsq + (size_t)row * 16);
.LBB0_1880:
	s_andn2_b64 vcc, exec, s[38:39]
	s_cbranch_vccnz .LBB0_1882
	s_waitcnt lgkmcnt(0)
	v_mov_b32_e32 v82, v169

;     __device__ __forceinline__ void operator()(const f32x4 (&acc)[2][2][4][2], const Unit& u, int wr, int wc, int fr_, int fq_) const {
;     ...
;                 const int row = u.pm * 256 + ai * 128 + wr * 64 + m * 16 + fr;
;                 const float rs = u.pm == pm0 ? rtab[ai * 128 + wr * 64 + m * 16 + fr] : rstd16(rsq + (size_t)row * 16);
.LBB0_1884:
	s_andn2_b64 vcc, exec, s[38:39]
	s_cbranch_vccnz .LBB0_1886
	v_lshl_add_u32 v66, v148, 2, s61
	s_waitcnt lgkmcnt(0)
	v_mov_b32_e32 v66, v170

;     __device__ __forceinline__ void operator()(const f32x4 (&acc)[2][2][4][2], const Unit& u, int wr, int wc, int fr_, int fq_) const {
;     ...
;                 const int row = u.pm * 256 + ai * 128 + wr * 64 + m * 16 + fr;
;                 const float rs = u.pm == pm0 ? rtab[ai * 128 + wr * 64 + m * 16 + fr] : rstd16(rsq + (size_t)row * 16);
.LBB0_1888:
	s_andn2_b64 vcc, exec, s[38:39]
	s_cbranch_vccnz .LBB0_1890
	s_waitcnt lgkmcnt(0)
	v_mov_b32_e32 v50, v171

;     __device__ __forceinline__ void operator()(const f32x4 (&acc)[2][2][4][2], const Unit& u, int wr, int wc, int fr_, int fq_) const {
;     ...
;                 const int row = u.pm * 256 + ai * 128 + wr * 64 + m * 16 + fr;
;                 const float rs = u.pm == pm0 ? rtab[ai * 128 + wr * 64 + m * 16 + fr] : rstd16(rsq + (size_t)row * 16);
.LBB0_1892:
	s_andn2_b64 vcc, exec, s[38:39]
	s_cbranch_vccnz .LBB0_1894
	s_waitcnt lgkmcnt(0)
	v_mov_b32_e32 v34, v172

;     __device__ __forceinline__ void operator()(const f32x4 (&acc)[2][2][4][2], const Unit& u, int wr, int wc, int fr_, int fq_) const {
;     ...
;                 const int row = u.pm * 256 + ai * 128 + wr * 64 + m * 16 + fr;
;                 const float rs = u.pm == pm0 ? rtab[ai * 128 + wr * 64 + m * 16 + fr] : rstd16(rsq + (size_t)row * 16);
.LBB0_1896:
	s_andn2_b64 vcc, exec, s[38:39]
	s_cbranch_vccnz .LBB0_1898
	s_waitcnt lgkmcnt(0)
	v_mov_b32_e32 v18, v173
